# row-wise phases: parameter-vector loads hoisted to loop top with counted vmcnt (on top of GEMM half-step pipeline)
# speedup vs baseline: 1.0358x; 1.0125x over previous
.LBB0_14:
	v_add_u32_e32 v9, 0xffffc000, v0
	v_cmp_gt_i32_e32 vcc, s69, v0
	v_mov_b32_e32 v11, s49
	v_mov_b32_e32 v24, s45
	v_cndmask_b32_e32 v23, 0, v1, vcc
	v_mov_b32_e32 v26, s48
	v_mov_b32_e32 v27, s44
	v_min_i32_e32 v28, 0x4000, v0
	v_cndmask_b32_e32 v22, v9, v0, vcc
	v_cndmask_b32_e32 v25, v11, v24, vcc
	v_cndmask_b32_e32 v24, v26, v27, vcc
	v_ashrrev_i32_e32 v9, 13, v28
	v_lshlrev_b64 v[22:23], 12, v[22:23]
	v_mul_hi_i32_i24_e32 v27, 0x6000, v9
	v_mul_i32_i24_e32 v26, 0x6000, v9
	v_lshl_add_u64 v[22:23], v[24:25], 0, v[22:23]
	v_lshl_add_u64 v[24:25], s[12:13], 0, v[26:27]
	v_lshl_add_u64 v[34:35], v[22:23], 0, v[192:193]
	global_load_dwordx4 v[18:21], v[2:3], off
	v_lshl_add_u64 v[46:47], v[24:25], 0, s[34:35]
	v_lshl_add_u64 v[48:49], v[24:25], 0, v[192:193]
	global_load_dwordx4 v[22:25], v[34:35], off
	global_load_dwordx4 v[26:29], v[34:35], off offset:1024
	global_load_dwordx4 v[30:33], v[34:35], off offset:2048
	s_nop 0
	global_load_dwordx4 v[34:37], v[34:35], off offset:3072
	v_lshl_add_u64 v[38:39], v[46:47], 0, v[192:193]
	global_load_dwordx4 v[38:41], v[38:39], off
	s_nop 0
	global_load_dwordx4 v[42:45], v[48:49], off
	v_lshl_add_u64 v[96:97], v[46:47], 0, v[192:193]
	global_load_dwordx4 v[100:103], v[2:3], off offset:1024
	global_load_dwordx4 v[112:115], v[96:97], off offset:1024
	global_load_dwordx4 v[124:127], v[48:49], off offset:1024
	global_load_dwordx4 v[104:107], v[2:3], off offset:2048
	global_load_dwordx4 v[116:119], v[96:97], off offset:2048
	global_load_dwordx4 v[128:131], v[48:49], off offset:2048
	global_load_dwordx4 v[108:111], v[2:3], off offset:3072
	global_load_dwordx4 v[120:123], v[96:97], off offset:3072
	global_load_dwordx4 v[132:135], v[48:49], off offset:3072
	v_mov_b32_e32 v7, v193
	v_lshl_add_u64 v[50:51], v[46:47], 0, v[6:7]
	v_mov_b32_e32 v11, v193
	s_movk_i32 s2, 0x41ff
	v_lshl_add_u64 v[0:1], v[0:1], 0, s[38:39]
	v_cmp_lt_i32_e32 vcc, s2, v0
	s_or_b64 s[42:43], vcc, s[42:43]
	s_waitcnt vmcnt(14)
	v_mul_f32_e32 v7, v23, v23
	s_waitcnt vmcnt(13)
	v_mul_f32_e32 v9, v27, v27
	s_waitcnt vmcnt(12)
	v_mov_b32_e32 v54, v31
	s_waitcnt vmcnt(11)
	v_mov_b32_e32 v55, v35
	v_mov_b32_e32 v52, v30
	v_mov_b32_e32 v53, v34
	v_fmac_f32_e32 v7, v22, v22
	v_fmac_f32_e32 v9, v26, v26
	v_pk_mul_f32 v[54:55], v[54:55], v[54:55]
	v_mov_b32_e32 v56, v32
	v_mov_b32_e32 v57, v36
	v_fmac_f32_e32 v7, v24, v24
	v_fmac_f32_e32 v9, v28, v28
	v_pk_fma_f32 v[52:53], v[52:53], v[52:53], v[54:55]
	v_mov_b32_e32 v58, v33
	v_mov_b32_e32 v59, v37
	v_fmac_f32_e32 v7, v25, v25
	v_fmac_f32_e32 v9, v29, v29
	v_pk_fma_f32 v[52:53], v[56:57], v[56:57], v[52:53]
	v_add_f32_e32 v7, v7, v9
	v_pk_fma_f32 v[52:53], v[58:59], v[58:59], v[52:53]
	s_waitcnt vmcnt(10)
	v_pk_add_f32 v[38:39], v[38:39], 1.0 op_sel_hi:[1,0]
	v_add_f32_e32 v7, v7, v52
	v_add_f32_e32 v7, v7, v53
	ds_bpermute_b32 v9, v12, v7
	v_pk_add_f32 v[40:41], v[40:41], 1.0 op_sel_hi:[1,0]
	s_waitcnt lgkmcnt(0)
	v_add_f32_e32 v7, v7, v9
	ds_bpermute_b32 v9, v13, v7
	s_waitcnt lgkmcnt(0)
	v_add_f32_e32 v7, v7, v9
	ds_bpermute_b32 v9, v14, v7
	s_waitcnt lgkmcnt(0)
	v_add_f32_e32 v7, v7, v9
	ds_bpermute_b32 v9, v15, v7
	s_waitcnt lgkmcnt(0)
	v_add_f32_e32 v7, v7, v9
	ds_bpermute_b32 v9, v16, v7
	s_waitcnt lgkmcnt(0)
	v_add_f32_e32 v7, v7, v9
	ds_bpermute_b32 v9, v17, v7
	s_waitcnt lgkmcnt(0)
	v_add_f32_e32 v7, v7, v9
	v_fmamk_f32 v7, v7, 0x3a800000, v221
	v_rsq_f32_e32 v52, v7
	v_mov_b32_e32 v9, v193
	v_pk_mul_f32 v[22:23], v[22:23], v[52:53] op_sel_hi:[1,0]
	v_pk_mul_f32 v[24:25], v[24:25], v[52:53] op_sel_hi:[1,0]
	v_pk_mul_f32 v[18:19], v[18:19], v[22:23]
	v_pk_mul_f32 v[20:21], v[20:21], v[24:25]
	s_waitcnt vmcnt(9)
	v_pk_fma_f32 v[18:19], v[38:39], v[18:19], v[42:43]
	v_pk_fma_f32 v[20:21], v[40:41], v[20:21], v[44:45]
	v_cvt_pk_bf16_f32 v18, v18, v19
	v_cvt_pk_bf16_f32 v19, v20, v21
	global_store_dwordx2 v[4:5], v[18:19], off
	s_nop 0
	s_nop 0
	s_nop 0
	s_nop 0
	v_pk_mul_f32 v[26:27], v[26:27], v[52:53] op_sel_hi:[1,0]
	v_pk_mul_f32 v[28:29], v[28:29], v[52:53] op_sel_hi:[1,0]
	v_lshl_add_u64 v[42:43], v[46:47], 0, v[8:9]
	v_pk_mul_f32 v[30:31], v[30:31], v[52:53] op_sel_hi:[1,0]
	v_pk_mul_f32 v[32:33], v[32:33], v[52:53] op_sel_hi:[1,0]
	s_waitcnt vmcnt(9)
	v_pk_mul_f32 v[18:19], v[100:101], v[26:27]
	s_waitcnt vmcnt(8)
	v_pk_add_f32 v[22:23], v[112:113], 1.0 op_sel_hi:[1,0]
	v_pk_mul_f32 v[20:21], v[102:103], v[28:29]
	v_pk_add_f32 v[24:25], v[114:115], 1.0 op_sel_hi:[1,0]
	s_waitcnt vmcnt(7)
	v_pk_fma_f32 v[18:19], v[22:23], v[18:19], v[124:125]
	v_pk_fma_f32 v[20:21], v[24:25], v[20:21], v[126:127]
	v_cvt_pk_bf16_f32 v18, v18, v19
	v_cvt_pk_bf16_f32 v19, v20, v21
	global_store_dwordx2 v[4:5], v[18:19], off offset:512
	s_nop 0
	s_nop 0
	s_nop 0
	s_nop 0
	v_lshl_add_u64 v[38:39], v[46:47], 0, v[10:11]
	s_waitcnt vmcnt(7)
	v_pk_mul_f32 v[18:19], v[30:31], v[104:105]
	s_waitcnt vmcnt(6)
	v_pk_add_f32 v[22:23], v[116:117], 1.0 op_sel_hi:[1,0]
	v_pk_mul_f32 v[20:21], v[32:33], v[106:107]
	v_pk_add_f32 v[24:25], v[118:119], 1.0 op_sel_hi:[1,0]
	s_waitcnt vmcnt(5)
	v_pk_fma_f32 v[18:19], v[18:19], v[22:23], v[128:129]
	v_pk_fma_f32 v[20:21], v[20:21], v[24:25], v[130:131]
	v_cvt_pk_bf16_f32 v18, v18, v19
	v_cvt_pk_bf16_f32 v19, v20, v21
	global_store_dwordx2 v[4:5], v[18:19], off offset:1024
	s_nop 0
	s_nop 0
	s_nop 0
	s_nop 0
	v_pk_mul_f32 v[30:31], v[34:35], v[52:53] op_sel_hi:[1,0]
	v_pk_mul_f32 v[32:33], v[36:37], v[52:53] op_sel_hi:[1,0]
	s_waitcnt vmcnt(5)
	v_pk_mul_f32 v[18:19], v[30:31], v[108:109]
	s_waitcnt vmcnt(4)
	v_pk_add_f32 v[22:23], v[120:121], 1.0 op_sel_hi:[1,0]
	v_pk_mul_f32 v[20:21], v[32:33], v[110:111]
	v_pk_add_f32 v[24:25], v[122:123], 1.0 op_sel_hi:[1,0]
	s_waitcnt vmcnt(3)
	v_pk_fma_f32 v[18:19], v[18:19], v[22:23], v[132:133]
	v_pk_fma_f32 v[20:21], v[20:21], v[24:25], v[134:135]
	v_cvt_pk_bf16_f32 v18, v18, v19
	v_cvt_pk_bf16_f32 v19, v20, v21
	global_store_dwordx2 v[4:5], v[18:19], off offset:1536
	v_lshl_add_u64 v[4:5], v[4:5], 0, s[40:41]
	s_andn2_b64 exec, exec, s[42:43]
	s_cbranch_execnz .LBB0_14

.LBB0_28:
	v_lshl_add_u64 v[0:1], v[32:33], 0, v[30:31]
	global_load_dwordx2 v[12:13], v[0:1], off
	global_load_dwordx2 v[14:15], v[0:1], off offset:1536
	global_load_dwordx2 v[36:37], v[0:1], off offset:512
	global_load_dwordx2 v[38:39], v[0:1], off offset:1024
	v_readlane_b32 s8, v254, 9
	v_readlane_b32 s48, v254, 38
	v_readlane_b32 s20, v254, 21
	v_readlane_b32 s21, v254, 22
	v_readlane_b32 s52, v254, 42
	v_readlane_b32 s53, v254, 43
	v_cmp_gt_i32_e32 vcc, s68, v16
	v_mov_b32_e32 v8, s21
	v_mov_b32_e32 v9, s53
	v_mov_b32_e32 v10, s20
	v_mov_b32_e32 v11, s52
	v_min_i32_e32 v40, 0x4000, v16
	v_readlane_b32 s12, v254, 13
	v_readlane_b32 s13, v254, 14
	v_cndmask_b32_e32 v9, v8, v9, vcc
	v_cndmask_b32_e32 v8, v10, v11, vcc
	v_ashrrev_i32_e32 v10, 13, v40
	s_mul_i32 s3, s24, 3
	v_add_u32_e32 v4, 0xffffc000, v16
	v_readlane_b32 s10, v254, 11
	v_readlane_b32 s11, v254, 12
	v_mov_b64_e32 v[6:7], s[12:13]
	v_add_u32_e32 v40, s3, v10
	v_cndmask_b32_e32 v5, 0, v17, vcc
	v_cndmask_b32_e32 v4, v4, v16, vcc
	v_mad_i64_i32 v[6:7], s[10:11], v40, s67, v[6:7]
	v_lshlrev_b64 v[4:5], 12, v[4:5]
	s_mov_b64 s[10:11], 0x5000
	v_lshlrev_b32_e32 v192, 2, v18
	v_lshl_add_u64 v[4:5], v[8:9], 0, v[4:5]
	v_lshl_add_u64 v[56:57], v[6:7], 0, s[10:11]
	global_load_dwordx4 v[0:3], v[26:27], off
	v_lshl_add_u64 v[54:55], v[4:5], 0, v[192:193]
	v_lshl_add_u64 v[8:9], v[56:57], 0, v[192:193]
	global_load_dwordx4 v[4:7], v[54:55], off
	s_andn2_b64 vcc, exec, s[38:39]
	global_load_dwordx4 v[8:11], v[8:9], off
	v_lshl_add_u64 v[96:97], v[56:57], 0, v[192:193]
	global_load_dwordx4 v[100:103], v[54:55], off offset:1024
	global_load_dwordx4 v[112:115], v[26:27], off offset:1024
	global_load_dwordx4 v[124:127], v[96:97], off offset:1024
	global_load_dwordx4 v[104:107], v[54:55], off offset:2048
	global_load_dwordx4 v[116:119], v[26:27], off offset:2048
	global_load_dwordx4 v[128:131], v[96:97], off offset:2048
	global_load_dwordx4 v[120:123], v[26:27], off offset:3072
	global_load_dwordx4 v[108:111], v[54:55], off offset:3072
	global_load_dwordx4 v[132:135], v[96:97], off offset:3072
	v_readlane_b32 s9, v254, 10
	v_readlane_b32 s14, v254, 15
	v_readlane_b32 s15, v254, 16
	v_readlane_b32 s16, v254, 17
	v_readlane_b32 s17, v254, 18
	v_readlane_b32 s18, v254, 19
	v_readlane_b32 s19, v254, 20
	v_readlane_b32 s22, v254, 23
	v_readlane_b32 s23, v254, 24
	v_readlane_b32 s49, v254, 39
	v_readlane_b32 s50, v254, 40
	v_readlane_b32 s51, v254, 41
	v_readlane_b32 s54, v254, 44
	v_readlane_b32 s55, v254, 45
	v_readlane_b32 s56, v254, 46
	v_readlane_b32 s57, v254, 47
	v_readlane_b32 s58, v254, 48
	v_readlane_b32 s59, v254, 49
	v_readlane_b32 s60, v254, 50
	v_readlane_b32 s61, v254, 51
	v_readlane_b32 s62, v254, 52
	v_readlane_b32 s63, v254, 53
	s_waitcnt vmcnt(15)
	v_lshlrev_b32_e32 v52, 16, v12
	v_and_b32_e32 v53, 0xffff0000, v12
	s_waitcnt vmcnt(13)
	v_lshlrev_b32_e32 v62, 16, v36
	v_and_b32_e32 v63, 0xffff0000, v36
	s_waitcnt vmcnt(12)
	v_and_b32_e32 v67, 0xffff0000, v38
	v_and_b32_e32 v69, 0xffff0000, v14
	v_lshlrev_b32_e32 v50, 16, v13
	v_and_b32_e32 v51, 0xffff0000, v13
	v_and_b32_e32 v59, 0xffff0000, v15
	v_lshlrev_b32_e32 v58, 16, v15
	v_lshlrev_b32_e32 v60, 16, v37
	v_and_b32_e32 v61, 0xffff0000, v37
	v_lshlrev_b32_e32 v64, 16, v39
	v_and_b32_e32 v65, 0xffff0000, v39
	v_lshlrev_b32_e32 v66, 16, v38
	v_lshlrev_b32_e32 v68, 16, v14
	v_pk_mul_f32 v[14:15], v[52:53], v[52:53]
	v_pk_mul_f32 v[38:39], v[62:63], v[62:63]
	v_mov_b32_e32 v70, v67
	v_mov_b32_e32 v71, v69
	v_pk_mul_f32 v[12:13], v[50:51], v[50:51]
	v_pk_mul_f32 v[36:37], v[60:61], v[60:61]
	v_mov_b32_e32 v46, v66
	v_mov_b32_e32 v47, v68
	v_pk_mul_f32 v[70:71], v[70:71], v[70:71]
	v_add_f32_e32 v38, v38, v39
	v_add_f32_e32 v39, v14, v15
	v_mov_b32_e32 v42, v64
	v_mov_b32_e32 v43, v58
	v_pk_fma_f32 v[14:15], v[46:47], v[46:47], v[70:71]
	v_add_f32_e32 v36, v36, v38
	v_add_f32_e32 v12, v12, v39
	v_mov_b32_e32 v44, v65
	v_mov_b32_e32 v45, v59
	v_pk_fma_f32 v[14:15], v[42:43], v[42:43], v[14:15]
	v_add_f32_e32 v36, v37, v36
	v_add_f32_e32 v37, v13, v12
	v_pk_fma_f32 v[12:13], v[44:45], v[44:45], v[14:15]
	v_add_f32_e32 v14, v37, v36
	v_add_f32_e32 v12, v14, v12
	v_add_f32_e32 v12, v12, v13
	ds_bpermute_b32 v13, v19, v12
	v_lshlrev_b32_e32 v42, 2, v20
	v_mov_b32_e32 v43, v193
	s_nop 0
	v_lshlrev_b32_e32 v38, 2, v22
	s_waitcnt lgkmcnt(0)
	v_add_f32_e32 v12, v12, v13
	ds_bpermute_b32 v13, v21, v12
	v_mov_b32_e32 v39, v193
	v_lshlrev_b32_e32 v36, 2, v24
	v_mov_b32_e32 v37, v193
	s_waitcnt lgkmcnt(0)
	v_add_f32_e32 v12, v12, v13
	ds_bpermute_b32 v13, v23, v12
	s_waitcnt lgkmcnt(0)
	v_add_f32_e32 v12, v12, v13
	ds_bpermute_b32 v13, v25, v12
	s_waitcnt lgkmcnt(0)
	v_add_f32_e32 v12, v12, v13
	ds_bpermute_b32 v13, v41, v12
	s_waitcnt lgkmcnt(0)
	v_add_f32_e32 v12, v12, v13
	ds_bpermute_b32 v13, v48, v12
	s_waitcnt lgkmcnt(0)
	v_add_f32_e32 v12, v12, v13
	v_fmamk_f32 v12, v12, 0x3a800000, v221
	v_rsq_f32_e32 v70, v12
	s_nop 0
	v_pk_mul_f32 v[12:13], v[70:71], v[52:53] op_sel_hi:[0,1]
	v_pk_mul_f32 v[14:15], v[70:71], v[50:51] op_sel_hi:[0,1]
	s_waitcnt vmcnt(11)
	v_pk_mul_f32 v[0:1], v[0:1], v[12:13]
	v_pk_mul_f32 v[2:3], v[2:3], v[14:15]
	s_waitcnt vmcnt(9)
	v_pk_fma_f32 v[12:13], v[8:9], v[0:1], v[4:5]
	v_pk_fma_f32 v[14:15], v[10:11], v[2:3], v[6:7]
	global_store_dwordx4 v[54:55], v[12:15], off
	s_nop 0
	v_lshl_add_u64 v[4:5], v[56:57], 0, v[42:43]
	s_nop 0
	v_pk_mul_f32 v[8:9], v[70:71], v[62:63] op_sel_hi:[0,1]
	v_pk_mul_f32 v[10:11], v[70:71], v[60:61] op_sel_hi:[0,1]
	s_nop 0
	v_pk_mul_f32 v[60:61], v[70:71], v[66:67] op_sel_hi:[0,1]
	v_pk_mul_f32 v[62:63], v[70:71], v[64:65] op_sel_hi:[0,1]
	v_pk_mul_f32 v[58:59], v[70:71], v[58:59] op_sel_hi:[0,1]
	s_waitcnt vmcnt(8)
	v_pk_mul_f32 v[0:1], v[112:113], v[8:9]
	v_pk_mul_f32 v[2:3], v[114:115], v[10:11]
	s_waitcnt vmcnt(7)
	v_pk_fma_f32 v[8:9], v[124:125], v[0:1], v[100:101]
	v_pk_fma_f32 v[10:11], v[126:127], v[2:3], v[102:103]
	global_store_dwordx4 v[54:55], v[8:11], off offset:1024
	s_nop 0
	v_lshl_add_u64 v[4:5], v[56:57], 0, v[38:39]
	s_nop 0
	s_waitcnt vmcnt(6)
	v_pk_mul_f32 v[0:1], v[116:117], v[60:61]
	v_pk_mul_f32 v[2:3], v[118:119], v[62:63]
	s_waitcnt vmcnt(5)
	v_pk_fma_f32 v[4:5], v[128:129], v[0:1], v[104:105]
	v_pk_fma_f32 v[6:7], v[130:131], v[2:3], v[106:107]
	global_store_dwordx4 v[54:55], v[4:7], off offset:2048
	s_nop 0
	v_lshl_add_u64 v[50:51], v[56:57], 0, v[36:37]
	s_nop 0
	v_pk_mul_f32 v[56:57], v[70:71], v[68:69] op_sel_hi:[0,1]
	s_nop 0
	s_waitcnt vmcnt(5)
	v_pk_mul_f32 v[0:1], v[56:57], v[120:121]
	v_pk_mul_f32 v[2:3], v[58:59], v[122:123]
	s_waitcnt vmcnt(3)
	v_pk_fma_f32 v[0:1], v[132:133], v[0:1], v[108:109]
	v_pk_fma_f32 v[2:3], v[134:135], v[2:3], v[110:111]
	global_store_dwordx4 v[54:55], v[0:3], off offset:3072
	s_cbranch_vccnz .LBB0_27
	v_pk_mul_f32 v[44:45], v[12:13], v[12:13]
	v_pk_mul_f32 v[46:47], v[14:15], v[14:15]
	v_add_f32_e32 v44, v44, v45
	v_add_f32_e32 v44, v46, v44
	v_pk_mul_f32 v[50:51], v[8:9], v[8:9]
	v_add_f32_e32 v44, v47, v44
	v_add_f32_e32 v44, v50, v44
	v_pk_mul_f32 v[52:53], v[10:11], v[10:11]
	v_add_f32_e32 v44, v51, v44
	v_add_f32_e32 v44, v52, v44
	v_pk_mul_f32 v[54:55], v[4:5], v[4:5]
	v_add_f32_e32 v44, v53, v44
	v_add_f32_e32 v44, v54, v44
	v_pk_mul_f32 v[56:57], v[6:7], v[6:7]
	v_add_f32_e32 v44, v55, v44
	v_add_f32_e32 v44, v56, v44
	v_pk_mul_f32 v[58:59], v[0:1], v[0:1]
	v_add_f32_e32 v44, v57, v44
	v_add_f32_e32 v44, v58, v44
	v_pk_mul_f32 v[60:61], v[2:3], v[2:3]
	v_add_f32_e32 v44, v59, v44
	v_add_f32_e32 v44, v60, v44
	v_add_f32_e32 v44, v61, v44
	ds_bpermute_b32 v45, v19, v44
	v_readlane_b32 s8, v254, 9
	v_readlane_b32 s12, v254, 13
	v_readlane_b32 s13, v254, 14
	v_add_u32_e32 v40, 3, v40
	s_waitcnt lgkmcnt(0)
	v_add_f32_e32 v44, v44, v45
	ds_bpermute_b32 v45, v21, v44
	v_readlane_b32 s10, v254, 11
	v_readlane_b32 s11, v254, 12
	global_load_dwordx4 v[50:53], v[28:29], off
	v_readlane_b32 s9, v254, 10
	s_waitcnt lgkmcnt(0)
	v_add_f32_e32 v44, v44, v45
	ds_bpermute_b32 v45, v23, v44
	v_readlane_b32 s14, v254, 15
	v_readlane_b32 s15, v254, 16
	v_readlane_b32 s16, v254, 17
	v_readlane_b32 s17, v254, 18
	s_waitcnt lgkmcnt(0)
	v_add_f32_e32 v44, v44, v45
	ds_bpermute_b32 v45, v25, v44
	v_readlane_b32 s18, v254, 19
	v_readlane_b32 s19, v254, 20
	v_readlane_b32 s20, v254, 21
	v_readlane_b32 s21, v254, 22
	s_waitcnt lgkmcnt(0)
	v_add_f32_e32 v44, v44, v45
	ds_bpermute_b32 v45, v41, v44
	v_readlane_b32 s22, v254, 23
	v_readlane_b32 s23, v254, 24
	s_waitcnt lgkmcnt(0)
	v_add_f32_e32 v44, v44, v45
	ds_bpermute_b32 v45, v48, v44
	s_waitcnt lgkmcnt(0)
	v_add_f32_e32 v49, v44, v45
	v_mov_b64_e32 v[44:45], s[12:13]
	v_mad_i64_i32 v[44:45], s[10:11], v40, s67, v[44:45]
	v_lshl_add_u64 v[46:47], v[44:45], 0, s[34:35]
	v_lshl_add_u64 v[54:55], v[46:47], 0, v[192:193]
	global_load_dwordx4 v[54:57], v[54:55], off
	v_lshl_add_u64 v[44:45], v[44:45], 0, v[192:193]
	global_load_dwordx4 v[58:61], v[44:45], off
	v_lshl_add_u64 v[98:99], v[46:47], 0, v[192:193]
	global_load_dwordx4 v[140:143], v[28:29], off offset:1024
	global_load_dwordx4 v[152:155], v[98:99], off offset:1024
	global_load_dwordx4 v[164:167], v[44:45], off offset:1024
	global_load_dwordx4 v[144:147], v[28:29], off offset:2048
	global_load_dwordx4 v[156:159], v[98:99], off offset:2048
	global_load_dwordx4 v[168:171], v[44:45], off offset:2048
	global_load_dwordx4 v[148:151], v[28:29], off offset:3072
	global_load_dwordx4 v[160:163], v[98:99], off offset:3072
	global_load_dwordx4 v[172:175], v[44:45], off offset:3072
	v_fmamk_f32 v40, v49, 0x3a800000, v221
	v_rsq_f32_e32 v40, v40
	s_nop 0
	v_pk_mul_f32 v[12:13], v[12:13], v[40:41] op_sel_hi:[1,0]
	v_pk_mul_f32 v[14:15], v[14:15], v[40:41] op_sel_hi:[1,0]
	v_pk_mul_f32 v[8:9], v[8:9], v[40:41] op_sel_hi:[1,0]
	v_pk_mul_f32 v[10:11], v[10:11], v[40:41] op_sel_hi:[1,0]
	v_pk_mul_f32 v[4:5], v[4:5], v[40:41] op_sel_hi:[1,0]
	v_pk_mul_f32 v[6:7], v[6:7], v[40:41] op_sel_hi:[1,0]
	v_pk_mul_f32 v[0:1], v[0:1], v[40:41] op_sel_hi:[1,0]
	v_pk_mul_f32 v[2:3], v[2:3], v[40:41] op_sel_hi:[1,0]
	s_waitcnt vmcnt(11)
	v_pk_mul_f32 v[12:13], v[50:51], v[12:13]
	v_pk_mul_f32 v[14:15], v[52:53], v[14:15]
	s_waitcnt vmcnt(10)
	v_pk_add_f32 v[50:51], v[54:55], 1.0 op_sel_hi:[1,0]
	s_waitcnt vmcnt(9)
	v_pk_fma_f32 v[12:13], v[50:51], v[12:13], v[58:59]
	v_pk_add_f32 v[50:51], v[56:57], 1.0 op_sel_hi:[1,0]
	s_nop 0
	v_pk_fma_f32 v[14:15], v[50:51], v[14:15], v[60:61]
	v_cvt_pk_bf16_f32 v50, v12, v13
	v_cvt_pk_bf16_f32 v51, v14, v15
	v_lshl_add_u64 v[12:13], v[34:35], 0, v[30:31]
	global_store_dwordx2 v[12:13], v[50:51], off
	s_nop 0
	v_lshl_add_u64 v[14:15], v[46:47], 0, v[42:43]
	s_nop 0
	s_nop 0
	s_waitcnt vmcnt(9)
	v_pk_mul_f32 v[8:9], v[8:9], v[140:141]
	s_waitcnt vmcnt(8)
	v_pk_add_f32 v[14:15], v[152:153], 1.0 op_sel_hi:[1,0]
	v_pk_mul_f32 v[10:11], v[10:11], v[142:143]
	s_waitcnt vmcnt(7)
	v_pk_fma_f32 v[8:9], v[8:9], v[14:15], v[164:165]
	v_pk_add_f32 v[14:15], v[154:155], 1.0 op_sel_hi:[1,0]
	v_cvt_pk_bf16_f32 v8, v8, v9
	v_pk_fma_f32 v[10:11], v[10:11], v[14:15], v[166:167]
	v_lshl_add_u64 v[14:15], v[46:47], 0, v[38:39]
	v_cvt_pk_bf16_f32 v9, v10, v11
	global_store_dwordx2 v[12:13], v[8:9], off offset:512
	s_nop 0
	s_nop 0
	s_nop 0
	s_nop 0
	s_waitcnt vmcnt(7)
	v_pk_mul_f32 v[4:5], v[4:5], v[144:145]
	s_waitcnt vmcnt(6)
	v_pk_add_f32 v[8:9], v[156:157], 1.0 op_sel_hi:[1,0]
	v_pk_mul_f32 v[6:7], v[6:7], v[146:147]
	s_waitcnt vmcnt(5)
	v_pk_fma_f32 v[4:5], v[4:5], v[8:9], v[168:169]
	v_pk_add_f32 v[8:9], v[158:159], 1.0 op_sel_hi:[1,0]
	v_cvt_pk_bf16_f32 v4, v4, v5
	v_pk_fma_f32 v[6:7], v[6:7], v[8:9], v[170:171]
	v_lshl_add_u64 v[8:9], v[46:47], 0, v[36:37]
	v_cvt_pk_bf16_f32 v5, v6, v7
	global_store_dwordx2 v[12:13], v[4:5], off offset:1024
	s_nop 0
	s_nop 0
	s_nop 0
	s_nop 0
	s_nop 0
	s_waitcnt vmcnt(5)
	v_pk_mul_f32 v[0:1], v[0:1], v[148:149]
	s_waitcnt vmcnt(4)
	v_pk_add_f32 v[4:5], v[160:161], 1.0 op_sel_hi:[1,0]
	v_pk_mul_f32 v[2:3], v[2:3], v[150:151]
	s_waitcnt vmcnt(3)
	v_pk_fma_f32 v[0:1], v[0:1], v[4:5], v[172:173]
	v_pk_add_f32 v[4:5], v[162:163], 1.0 op_sel_hi:[1,0]
	v_cvt_pk_bf16_f32 v0, v0, v1
	v_pk_fma_f32 v[2:3], v[2:3], v[4:5], v[174:175]
	s_nop 0
	v_cvt_pk_bf16_f32 v1, v2, v3
	global_store_dwordx2 v[12:13], v[0:1], off offset:1536
	s_branch .LBB0_27

.LBB0_71:
	v_readlane_b32 s8, v253, 56
	v_readlane_b32 s12, v253, 60
	v_cmp_gt_i32_e64 s[0:1], s3, v24
	v_mov_b32_e32 v3, s8
	s_mov_b32 s8, s54
	v_readlane_b32 s48, v254, 9
	v_readlane_b32 s9, v253, 57
	v_readlane_b32 s10, v253, 58
	v_readlane_b32 s11, v253, 59
	v_readlane_b32 s13, v253, 61
	v_readlane_b32 s14, v253, 62
	v_readlane_b32 s15, v253, 63
	v_readlane_b32 s16, v254, 0
	v_readlane_b32 s17, v254, 1
	v_readlane_b32 s18, v254, 2
	v_readlane_b32 s19, v254, 3
	v_readlane_b32 s20, v254, 4
	v_readlane_b32 s21, v254, 5
	v_readlane_b32 s22, v254, 6
	v_readlane_b32 s23, v254, 7
	v_mov_b32_e32 v2, s12
	v_readlane_b32 s54, v254, 15
	v_cndmask_b32_e64 v2, v2, v3, s[0:1]
	v_mov_b32_e32 v3, s13
	v_mov_b32_e32 v4, s9
	s_mov_b32 s54, s8
	v_readlane_b32 s8, v254, 38
	v_readlane_b32 s61, v254, 22
	v_readlane_b32 s13, v254, 43
	v_cndmask_b32_e64 v3, v3, v4, s[0:1]
	v_readlane_b32 s60, v254, 21
	v_mov_b32_e32 v4, s61
	v_readlane_b32 s12, v254, 42
	v_mov_b32_e32 v5, s13
	v_add_u32_e32 v0, 0xffffc000, v24
	v_cndmask_b32_e64 v17, v4, v5, s[0:1]
	v_mov_b32_e32 v4, s60
	v_mov_b32_e32 v5, s12
	v_cndmask_b32_e64 v1, 0, v25, s[0:1]
	v_cndmask_b32_e64 v0, v0, v24, s[0:1]
	v_cndmask_b32_e64 v16, v4, v5, s[0:1]
	v_cndmask_b32_e32 v3, v17, v3, vcc
	v_cndmask_b32_e32 v2, v16, v2, vcc
	v_lshlrev_b64 v[18:19], 12, v[0:1]
	v_lshl_add_u64 v[0:1], v[2:3], 0, v[18:19]
	v_min_i32_e32 v2, 0x4000, v24
	v_readlane_b32 s52, v254, 13
	v_readlane_b32 s53, v254, 14
	v_ashrrev_i32_e32 v2, 13, v2
	s_mul_i32 s0, s54, 3
	v_add_u32_e32 v4, s0, v2
	v_mov_b64_e32 v[2:3], s[52:53]
	v_mad_i64_i32 v[42:43], s[0:1], v4, s67, v[2:3]
	v_lshl_add_u64 v[4:5], v[32:33], 0, v[30:31]
	v_lshl_add_u64 v[6:7], v[0:1], 0, v[192:193]
	global_load_dwordx2 v[54:55], v[4:5], off
	global_load_dwordx4 v[12:15], v[6:7], off
	global_load_dwordx2 v[58:59], v[4:5], off offset:512
	global_load_dwordx4 v[8:11], v[6:7], off offset:1024
	global_load_dwordx2 v[20:21], v[4:5], off offset:1024
	global_load_dwordx4 v[0:3], v[6:7], off offset:2048
	global_load_dwordx2 v[22:23], v[4:5], off offset:1536
	s_nop 0
	global_load_dwordx4 v[4:7], v[6:7], off offset:3072
	v_lshl_add_u64 v[96:97], v[42:43], 0, v[192:193]
	s_mov_b64 s[0:1], 0x2000
	v_lshl_add_u64 v[98:99], v[96:97], 0, s[0:1]
	s_mov_b64 s[0:1], 0x3000
	v_lshl_add_u64 v[100:101], v[96:97], 0, s[0:1]
	s_mov_b64 s[0:1], 0x4000
	v_lshl_add_u64 v[102:103], v[96:97], 0, s[0:1]
	global_load_dwordx4 v[104:107], v[98:99], off
	global_load_dwordx4 v[120:123], v[26:27], off
	global_load_dwordx4 v[108:111], v[98:99], off offset:1024
	global_load_dwordx4 v[124:127], v[26:27], off offset:1024
	global_load_dwordx4 v[112:115], v[98:99], off offset:2048
	global_load_dwordx4 v[128:131], v[26:27], off offset:2048
	global_load_dwordx4 v[116:119], v[98:99], off offset:3072
	global_load_dwordx4 v[132:135], v[26:27], off offset:3072
	global_load_dwordx4 v[136:139], v[102:103], off
	global_load_dwordx4 v[152:155], v[100:101], off
	global_load_dwordx4 v[168:171], v[28:29], off
	global_load_dwordx4 v[172:175], v[28:29], off offset:1024
	global_load_dwordx4 v[140:143], v[102:103], off offset:1024
	global_load_dwordx4 v[156:159], v[100:101], off offset:1024
	global_load_dwordx4 v[176:179], v[28:29], off offset:2048
	global_load_dwordx4 v[144:147], v[102:103], off offset:2048
	global_load_dwordx4 v[160:163], v[100:101], off offset:2048
	global_load_dwordx4 v[180:183], v[28:29], off offset:3072
	global_load_dwordx4 v[148:151], v[102:103], off offset:3072
	global_load_dwordx4 v[164:167], v[100:101], off offset:3072
	s_mov_b64 s[0:1], 0x2000
	v_lshl_add_u64 v[52:53], v[42:43], 0, s[0:1]
	v_lshl_add_u64 v[72:73], v[16:17], 0, v[18:19]
	v_lshl_add_u64 v[16:17], v[52:53], 0, v[192:193]
	v_mov_b32_e32 v37, v193
	s_mov_b64 s[0:1], 0x4000
	v_lshl_add_u64 v[24:25], v[24:25], 0, s[40:41]
	v_lshl_add_u64 v[32:33], v[32:33], 0, s[42:43]
	v_readlane_b32 s49, v254, 10
	v_readlane_b32 s50, v254, 11
	v_readlane_b32 s51, v254, 12
	v_readlane_b32 s55, v254, 16
	v_readlane_b32 s56, v254, 17
	v_readlane_b32 s57, v254, 18
	v_readlane_b32 s58, v254, 19
	v_readlane_b32 s59, v254, 20
	v_readlane_b32 s62, v254, 23
	v_readlane_b32 s63, v254, 24
	v_readlane_b32 s9, v254, 39
	v_readlane_b32 s10, v254, 40
	v_readlane_b32 s11, v254, 41
	v_readlane_b32 s14, v254, 44
	v_readlane_b32 s15, v254, 45
	v_readlane_b32 s16, v254, 46
	v_readlane_b32 s17, v254, 47
	v_readlane_b32 s18, v254, 48
	v_readlane_b32 s19, v254, 49
	v_readlane_b32 s20, v254, 50
	v_readlane_b32 s21, v254, 51
	v_readlane_b32 s22, v254, 52
	v_readlane_b32 s23, v254, 53
	s_waitcnt vmcnt(27)
	v_lshlrev_b32_e32 v62, 16, v54
	v_and_b32_e32 v63, 0xffff0000, v54
	s_waitcnt vmcnt(25)
	v_lshlrev_b32_e32 v76, 16, v58
	v_and_b32_e32 v77, 0xffff0000, v58
	s_waitcnt vmcnt(23)
	v_and_b32_e32 v50, 0xffff0000, v20
	v_lshlrev_b32_e32 v48, 16, v20
	s_waitcnt vmcnt(21)
	v_and_b32_e32 v51, 0xffff0000, v22
	v_lshlrev_b32_e32 v49, 16, v22
	v_lshlrev_b32_e32 v44, 16, v21
	v_and_b32_e32 v46, 0xffff0000, v21
	v_pk_mul_f32 v[20:21], v[50:51], v[50:51]
	v_lshlrev_b32_e32 v45, 16, v23
	v_pk_fma_f32 v[20:21], v[48:49], v[48:49], v[20:21]
	v_and_b32_e32 v47, 0xffff0000, v23
	v_pk_fma_f32 v[20:21], v[44:45], v[44:45], v[20:21]
	v_pk_mul_f32 v[74:75], v[62:63], v[62:63]
	v_pk_fma_f32 v[56:57], v[46:47], v[46:47], v[20:21]
	s_nop 0
	s_nop 0
	s_nop 0
	v_lshlrev_b32_e32 v60, 16, v55
	v_and_b32_e32 v61, 0xffff0000, v55
	v_pk_mul_f32 v[78:79], v[76:77], v[76:77]
	v_lshlrev_b32_e32 v80, 16, v59
	v_and_b32_e32 v81, 0xffff0000, v59
	v_pk_mul_f32 v[64:65], v[60:61], v[60:61]
	v_pk_mul_f32 v[58:59], v[80:81], v[80:81]
	v_add_f32_e32 v39, v78, v79
	v_add_f32_e32 v41, v74, v75
	v_add_f32_e32 v39, v58, v39
	v_add_f32_e32 v41, v64, v41
	v_add_f32_e32 v39, v59, v39
	v_add_f32_e32 v41, v65, v41
	v_add_f32_e32 v39, v41, v39
	v_add_f32_e32 v39, v39, v56
	v_add_f32_e32 v39, v39, v57
	ds_bpermute_b32 v41, v66, v39
	v_lshl_add_u64 v[54:55], v[72:73], 0, v[192:193]
	v_lshl_add_u64 v[72:73], v[52:53], 0, v[36:37]
	s_waitcnt lgkmcnt(0)
	v_add_f32_e32 v39, v39, v41
	ds_bpermute_b32 v41, v67, v39
	s_waitcnt lgkmcnt(0)
	v_add_f32_e32 v39, v39, v41
	ds_bpermute_b32 v41, v68, v39
	s_waitcnt lgkmcnt(0)
	v_add_f32_e32 v39, v39, v41
	ds_bpermute_b32 v41, v69, v39
	s_waitcnt lgkmcnt(0)
	v_add_f32_e32 v39, v39, v41
	ds_bpermute_b32 v41, v70, v39
	s_waitcnt lgkmcnt(0)
	v_add_f32_e32 v39, v39, v41
	ds_bpermute_b32 v41, v71, v39
	s_waitcnt lgkmcnt(0)
	v_add_f32_e32 v39, v39, v41
	v_fmamk_f32 v39, v39, 0x3a800000, v221
	v_rsq_f32_e32 v56, v39
	v_mov_b32_e32 v39, v193
	v_mov_b32_e32 v41, v193
	v_pk_mul_f32 v[58:59], v[56:57], v[62:63] op_sel_hi:[0,1]
	v_pk_mul_f32 v[62:63], v[56:57], v[76:77] op_sel_hi:[0,1]
	s_waitcnt vmcnt(18)
	v_pk_mul_f32 v[20:21], v[120:121], v[58:59]
	s_nop 0
	v_pk_fma_f32 v[12:13], v[104:105], v[20:21], v[12:13]
	v_pk_mul_f32 v[20:21], v[56:57], v[60:61] op_sel_hi:[0,1]
	v_pk_mul_f32 v[20:21], v[122:123], v[20:21]
	v_pk_mul_f32 v[16:17], v[12:13], v[12:13]
	v_pk_fma_f32 v[14:15], v[106:107], v[20:21], v[14:15]
	global_store_dwordx4 v[54:55], v[12:15], off
	s_nop 0
	s_nop 0
	v_mov_b32_e32 v72, v48
	v_mov_b32_e32 v73, v50
	v_pk_mul_f32 v[72:73], v[56:57], v[72:73] op_sel_hi:[0,1]
	v_pk_mul_f32 v[18:19], v[14:15], v[14:15]
	v_add_f32_e32 v16, v16, v17
	v_add_f32_e32 v16, v18, v16
	v_add_f32_e32 v16, v19, v16
	v_mov_b32_e32 v50, v49
	v_pk_mul_f32 v[48:49], v[56:57], v[50:51] op_sel_hi:[0,1]
	s_waitcnt vmcnt(17)
	v_pk_mul_f32 v[58:59], v[124:125], v[62:63]
	s_nop 0
	v_pk_fma_f32 v[8:9], v[108:109], v[58:59], v[8:9]
	v_pk_mul_f32 v[20:21], v[56:57], v[80:81] op_sel_hi:[0,1]
	v_pk_mul_f32 v[20:21], v[126:127], v[20:21]
	v_pk_mul_f32 v[62:63], v[8:9], v[8:9]
	v_pk_fma_f32 v[10:11], v[110:111], v[20:21], v[10:11]
	global_store_dwordx4 v[54:55], v[8:11], off offset:1024
	v_lshl_add_u64 v[20:21], v[52:53], 0, v[38:39]
	s_nop 0
	s_nop 0
	s_nop 0
	v_add_f32_e32 v16, v62, v16
	v_pk_mul_f32 v[64:65], v[10:11], v[10:11]
	v_add_f32_e32 v16, v63, v16
	v_add_f32_e32 v16, v64, v16
	v_add_f32_e32 v16, v65, v16
	s_waitcnt vmcnt(16)
	v_pk_mul_f32 v[58:59], v[128:129], v[72:73]
	s_nop 0
	v_pk_fma_f32 v[0:1], v[112:113], v[58:59], v[0:1]
	v_mov_b32_e32 v20, v44
	v_mov_b32_e32 v21, v46
	v_pk_mul_f32 v[20:21], v[56:57], v[20:21] op_sel_hi:[0,1]
	v_pk_mul_f32 v[20:21], v[130:131], v[20:21]
	v_pk_mul_f32 v[72:73], v[0:1], v[0:1]
	v_pk_fma_f32 v[2:3], v[114:115], v[20:21], v[2:3]
	global_store_dwordx4 v[54:55], v[0:3], off offset:2048
	v_lshl_add_u64 v[20:21], v[52:53], 0, v[40:41]
	s_nop 0
	s_nop 0
	s_nop 0
	v_add_f32_e32 v16, v72, v16
	v_pk_mul_f32 v[74:75], v[2:3], v[2:3]
	v_mov_b32_e32 v46, v45
	v_add_f32_e32 v16, v73, v16
	v_pk_mul_f32 v[44:45], v[56:57], v[46:47] op_sel_hi:[0,1]
	v_add_f32_e32 v16, v74, v16
	v_add_f32_e32 v16, v75, v16
	s_waitcnt vmcnt(15)
	v_pk_mul_f32 v[48:49], v[48:49], v[132:133]
	s_nop 0
	v_pk_fma_f32 v[4:5], v[116:117], v[48:49], v[4:5]
	v_pk_mul_f32 v[44:45], v[44:45], v[134:135]
	v_pk_mul_f32 v[20:21], v[4:5], v[4:5]
	v_pk_fma_f32 v[6:7], v[118:119], v[44:45], v[6:7]
	v_add_f32_e32 v16, v20, v16
	v_pk_mul_f32 v[22:23], v[6:7], v[6:7]
	v_add_f32_e32 v16, v21, v16
	v_add_f32_e32 v16, v22, v16
	v_add_f32_e32 v16, v23, v16
	ds_bpermute_b32 v17, v66, v16
	v_lshl_add_u64 v[44:45], v[42:43], 0, s[0:1]
	s_mov_b64 s[0:1], 0x3000
	global_store_dwordx4 v[54:55], v[4:7], off offset:3072
	v_lshl_add_u64 v[22:23], v[42:43], 0, s[0:1]
	s_waitcnt lgkmcnt(0)
	v_add_f32_e32 v16, v16, v17
	ds_bpermute_b32 v17, v67, v16
	v_lshl_add_u64 v[42:43], v[44:45], 0, v[192:193]
	s_nop 0
	v_lshl_add_u64 v[42:43], v[22:23], 0, v[192:193]
	s_nop 0
	s_waitcnt lgkmcnt(0)
	v_add_f32_e32 v16, v16, v17
	ds_bpermute_b32 v17, v68, v16
	v_lshl_add_u64 v[42:43], v[34:35], 0, v[30:31]
	v_cmp_le_i32_e64 s[0:1], s2, v24
	v_lshl_add_u64 v[34:35], v[34:35], 0, s[42:43]
	s_or_b64 s[44:45], s[0:1], s[44:45]
	s_waitcnt lgkmcnt(0)
	v_add_f32_e32 v16, v16, v17
	ds_bpermute_b32 v17, v69, v16
	s_waitcnt lgkmcnt(0)
	v_add_f32_e32 v16, v16, v17
	ds_bpermute_b32 v17, v70, v16
	s_waitcnt lgkmcnt(0)
	v_add_f32_e32 v16, v16, v17
	ds_bpermute_b32 v17, v71, v16
	s_waitcnt lgkmcnt(0)
	v_add_f32_e32 v16, v16, v17
	v_fmamk_f32 v16, v16, 0x3a800000, v221
	v_rsq_f32_e32 v20, v16
	s_nop 0
	v_pk_mul_f32 v[12:13], v[12:13], v[20:21] op_sel_hi:[1,0]
	v_pk_mul_f32 v[14:15], v[14:15], v[20:21] op_sel_hi:[1,0]
	v_pk_mul_f32 v[8:9], v[8:9], v[20:21] op_sel_hi:[1,0]
	v_pk_mul_f32 v[10:11], v[10:11], v[20:21] op_sel_hi:[1,0]
	v_pk_mul_f32 v[0:1], v[0:1], v[20:21] op_sel_hi:[1,0]
	v_pk_mul_f32 v[2:3], v[2:3], v[20:21] op_sel_hi:[1,0]
	v_pk_mul_f32 v[4:5], v[4:5], v[20:21] op_sel_hi:[1,0]
	s_waitcnt vmcnt(13)
	v_pk_mul_f32 v[12:13], v[168:169], v[12:13]
	v_pk_add_f32 v[16:17], v[136:137], 1.0 op_sel_hi:[1,0]
	v_pk_mul_f32 v[14:15], v[170:171], v[14:15]
	v_pk_fma_f32 v[12:13], v[16:17], v[12:13], v[152:153]
	v_pk_add_f32 v[16:17], v[138:139], 1.0 op_sel_hi:[1,0]
	v_cvt_pk_bf16_f32 v12, v12, v13
	v_pk_fma_f32 v[14:15], v[16:17], v[14:15], v[154:155]
	v_lshl_add_u64 v[16:17], v[44:45], 0, v[36:37]
	v_cvt_pk_bf16_f32 v13, v14, v15
	global_store_dwordx2 v[42:43], v[12:13], off
	s_nop 0
	v_lshl_add_u64 v[46:47], v[22:23], 0, v[36:37]
	s_nop 0
	s_waitcnt vmcnt(13)
	v_pk_mul_f32 v[8:9], v[172:173], v[8:9]
	s_nop 0
	s_waitcnt vmcnt(12)
	v_pk_add_f32 v[12:13], v[140:141], 1.0 op_sel_hi:[1,0]
	v_pk_mul_f32 v[10:11], v[174:175], v[10:11]
	v_lshl_add_u64 v[16:17], v[22:23], 0, v[38:39]
	s_waitcnt vmcnt(11)
	v_pk_fma_f32 v[8:9], v[12:13], v[8:9], v[156:157]
	v_pk_add_f32 v[12:13], v[142:143], 1.0 op_sel_hi:[1,0]
	v_cvt_pk_bf16_f32 v8, v8, v9
	v_pk_fma_f32 v[10:11], v[12:13], v[10:11], v[158:159]
	v_lshl_add_u64 v[12:13], v[44:45], 0, v[38:39]
	v_cvt_pk_bf16_f32 v9, v10, v11
	global_store_dwordx2 v[42:43], v[8:9], off offset:512
	s_nop 0
	s_waitcnt vmcnt(11)
	v_pk_mul_f32 v[0:1], v[176:177], v[0:1]
	s_nop 0
	v_pk_mul_f32 v[2:3], v[178:179], v[2:3]
	s_nop 0
	s_waitcnt vmcnt(10)
	v_pk_add_f32 v[8:9], v[144:145], 1.0 op_sel_hi:[1,0]
	v_lshl_add_u64 v[12:13], v[22:23], 0, v[40:41]
	s_waitcnt vmcnt(9)
	v_pk_fma_f32 v[0:1], v[8:9], v[0:1], v[160:161]
	v_pk_add_f32 v[8:9], v[146:147], 1.0 op_sel_hi:[1,0]
	v_cvt_pk_bf16_f32 v0, v0, v1
	v_pk_fma_f32 v[2:3], v[8:9], v[2:3], v[162:163]
	v_lshl_add_u64 v[8:9], v[44:45], 0, v[40:41]
	v_cvt_pk_bf16_f32 v1, v2, v3
	global_store_dwordx2 v[42:43], v[0:1], off offset:1024
	s_nop 0
	s_waitcnt vmcnt(9)
	v_pk_mul_f32 v[0:1], v[180:181], v[4:5]
	s_nop 0
	s_waitcnt vmcnt(8)
	v_pk_add_f32 v[4:5], v[148:149], 1.0 op_sel_hi:[1,0]
	s_nop 0
	s_waitcnt vmcnt(7)
	v_pk_fma_f32 v[0:1], v[4:5], v[0:1], v[164:165]
	v_pk_mul_f32 v[4:5], v[6:7], v[20:21] op_sel_hi:[1,0]
	v_cvt_pk_bf16_f32 v0, v0, v1
	v_pk_mul_f32 v[2:3], v[182:183], v[4:5]
	v_pk_add_f32 v[4:5], v[150:151], 1.0 op_sel_hi:[1,0]
	s_nop 0
	v_pk_fma_f32 v[2:3], v[4:5], v[2:3], v[166:167]
	s_nop 0
	v_cvt_pk_bf16_f32 v1, v2, v3
	global_store_dwordx2 v[42:43], v[0:1], off offset:1536
	s_andn2_b64 exec, exec, s[44:45]
	s_cbranch_execnz .LBB0_71
